# stack: layer-0 W2 early conversion at site 6 + static s_setprio for waves 4-7 in GEMM phases (flips deleted)
# speedup vs baseline: 1.0060x; 1.0060x over previous
; __device__ __forceinline__ unsigned pk_bf16(float lo, float hi) { unsigned r; asm volatile("v_cvt_pk_bf16_f32 %0, %1, %2" : "=v"(r) : "v"(lo), "v"(hi)); return r; }
; #define WT_LOAD() do { _Pragma("unroll") for (int i = 0; i < 16; ++i) rg[i] = sp ? sp[(size_t)(k0 + kq + i * 8) * ld] : 0.f; } while (0)
; __device__ __forceinline__ void phase_weights(int wv, const Params& p, int l, LAS unsigned char* lds, int first, int stride) {
;     ...
;     if (ti < 1536) { WT_DECODE(ti); WT_LOAD(); }
;     while (ti < 1536) {
;         bf16_t* cdst = dst + (size_t)n0 * K + k0; const int cK = K;
;         __syncthreads();
; #pragma unroll
;         for (int i = 0; i < 16; ++i) tile[(kq + i * 8) * 65 + nl] = rg[i];
;         ti += stride;
;         if (ti < 1536) { WT_DECODE(ti); WT_LOAD(); }
;         __syncthreads();
;         { const int nn = tid >> 3, ks = tid & 7; float v[16];
; #pragma unroll
;             for (int j = 0; j < 16; ++j) v[j] = tile[(ks * 16 + j) * 65 + nn];
;             u32x4 w0, w1; w0.x = pk_bf16(v[0], v[1]); w0.y = pk_bf16(v[2], v[3]); w0.z = pk_bf16(v[4], v[5]); w0.w = pk_bf16(v[6], v[7]);
;             w1.x = pk_bf16(v[8], v[9]); w1.y = pk_bf16(v[10], v[11]); w1.z = pk_bf16(v[12], v[13]); w1.w = pk_bf16(v[14], v[15]);
;             bf16_t* o = cdst + (size_t)nn * cK + ks * 16; *(u32x4*)o = w0; *(u32x4*)(o + 8) = w1; }
.LBB0_1163:
	s_setprio 0
	v_writelane_b32 v255, s24, 63
	v_readlane_b32 s24, v255, 3
	s_cmpk_lt_u32 s24, 128
	s_cbranch_scc1 .Lew_end_a
	s_cmpk_lg_u32 s44, 0x100
	s_cbranch_scc1 .Lew_end_a
	v_readlane_b32 s24, v255, 22
	s_cmp_lg_u32 s24, 0
	s_cbranch_scc1 .Lew_end_a
	v_writelane_b32 v255, s3, 43
	v_writelane_b32 v255, s6, 44
	v_writelane_b32 v255, s7, 45
	v_writelane_b32 v255, s14, 46
	v_writelane_b32 v255, s15, 47
	v_writelane_b32 v255, s16, 48
	v_writelane_b32 v255, s17, 49
	v_writelane_b32 v255, s18, 50
	v_writelane_b32 v255, s19, 51
	v_writelane_b32 v255, s22, 52
	v_writelane_b32 v255, s23, 53
	v_writelane_b32 v255, s26, 54
	v_writelane_b32 v255, s27, 55
	v_writelane_b32 v255, s30, 56
	v_writelane_b32 v255, s31, 57
	v_writelane_b32 v255, s36, 58
	v_writelane_b32 v255, s37, 59
	s_load_dwordx2 s[14:15], s[90:91], 0x98
	s_load_dwordx2 s[16:17], s[90:91], 0xa8
	v_mbcnt_lo_u32_b32 v2, -1, 0
	v_mbcnt_hi_u32_b32 v2, -1, v2
	v_and_b32_e32 v3, 15, v2
	v_lshrrev_b32_e32 v6, 4, v2
	v_lshlrev_b32_e32 v12, 4, v3
	v_lshl_add_u32 v12, v6, 16, v12
	v_mov_b32_e32 v13, 0
	v_mul_u32_u24_e32 v10, 0x5800, v3
	v_lshl_add_u32 v10, v6, 5, v10
	s_waitcnt lgkmcnt(0)
	v_mov_b32_e32 v4, s14
	v_mov_b32_e32 v5, s15
	v_lshl_add_u64 v[4:5], v[4:5], 0, v[12:13]
	s_add_u32 s16, s16, 0xc04c000
	s_addc_u32 s17, s17, 0
	v_readlane_b32 s24, v255, 7
	s_lshr_b32 s24, s24, 6
	v_readlane_b32 s3, v255, 3
	s_sub_i32 s3, s3, 128
	s_lshl_b32 s3, s3, 3
	s_add_i32 s3, s3, s24
